# weight conversion with 128x128 tiles (256 B dst pieces, 512 B src pieces), register transpose, two tiles in flight
# speedup vs baseline: 1.0033x; 1.0033x over previous
; #define LAS __attribute__((address_space(3)))
; __device__ __forceinline__ int opq_tid() { int t = threadIdx.x; asm volatile("" : "+v"(t)); return t; }
; __device__ __forceinline__ int opq_bid() { int b = blockIdx.x; asm volatile("" : "+s"(b)); return b; }
; __device__ __forceinline__ f32x4 ld_nt(const float* p) { return __builtin_nontemporal_load((const f32x4*)p); }
; __device__ __forceinline__ void convert_weight_v4(LAS unsigned char* lds, const float* W, bf16_t* Bt, int K, int Nsrc, int Ndst, const float* gain, int mode) {
;     LAS float* tile = (LAS float*)lds;
;     const int tid = opq_tid(), nkt = K / 64, nnt = Ndst / 256;
;     for (int t = opq_bid(); t < nkt * nnt; t += gridDim.x) {
;         const int k0 = (t % nkt) * 64, pn = t / nkt, n0 = pn * 256;
;         f32x4 v[8];
; #pragma unroll
;         for (int i = 0; i < 8; ++i) {
;             const int e = tid + i * 512, kk = e >> 6, n4 = e & 63;
;             const int n = (mode == 1) ? (n4 >> 5) * FF + pn * 128 + (n4 & 31) * 4 : n0 + n4 * 4;
;             v[i] = (f32x4){0.f, 0.f, 0.f, 0.f};
;             if (n < Nsrc) v[i] = ld_nt(W + (size_t)(k0 + kk) * Nsrc + n);
; __device__ __forceinline__ void prologue(LAS unsigned char* lds, const Params& P) {
;     ...
;     for (int l = 0; l < 2; ++l) {
;         convert_weight_v4(lds, in[10] + (size_t)l * D * 2 * FF, (bf16_t*)(ws + W_GU + (size_t)(l * 2 + 0) * W_GU_SZ), D, 2 * FF, 2 * FF, in[9] + l * D, 1);
;         convert_weight_v4(lds, in[14] + (size_t)l * D * 2 * FF, (bf16_t*)(ws + W_GU + (size_t)(l * 2 + 1) * W_GU_SZ), D, 2 * FF, 2 * FF, in[13] + l * D, 1);
.LBB0_17:
	s_load_dwordx16 s[36:51], s[0:1], 0x0
	v_writelane_b32 v255, s12, 3
	s_add_u32 s92, s88, 0x956a000
	s_addc_u32 s93, s89, 0
	s_cmp_lt_i32 s90, 1
	s_waitcnt lgkmcnt(0)
	v_writelane_b32 v255, s36, 4
	s_mov_b32 s5, 0
	s_nop 0
	v_writelane_b32 v255, s37, 5
	v_writelane_b32 v255, s38, 6
	v_writelane_b32 v255, s39, 7
	v_writelane_b32 v255, s40, 8
	v_writelane_b32 v255, s41, 9
	v_writelane_b32 v255, s42, 10
	v_writelane_b32 v255, s43, 11
	v_writelane_b32 v255, s44, 12
	v_writelane_b32 v255, s45, 13
	v_writelane_b32 v255, s46, 14
	v_writelane_b32 v255, s47, 15
	v_writelane_b32 v255, s48, 16
	v_writelane_b32 v255, s49, 17
	v_writelane_b32 v255, s50, 18
	v_writelane_b32 v255, s51, 19
	s_load_dwordx16 s[56:71], s[0:1], 0x40
	s_load_dwordx16 s[72:87], s[0:1], 0x80
	s_load_dwordx16 s[40:55], s[0:1], 0xc0
	s_cselect_b64 s[0:1], -1, 0
	s_cmp_gt_i32 s91, 0
	s_cselect_b64 s[2:3], -1, 0
	s_waitcnt lgkmcnt(0)
	v_writelane_b32 v255, s72, 20
	s_and_b64 s[2:3], s[0:1], s[2:3]
	s_andn2_b64 vcc, exec, s[2:3]
	v_writelane_b32 v255, s73, 21
	v_writelane_b32 v255, s74, 22
	v_writelane_b32 v255, s75, 23
	v_writelane_b32 v255, s76, 24
	v_writelane_b32 v255, s77, 25
	v_writelane_b32 v255, s78, 26
	v_writelane_b32 v255, s79, 27
	v_writelane_b32 v255, s80, 28
	v_writelane_b32 v255, s81, 29
	v_writelane_b32 v255, s82, 30
	v_writelane_b32 v255, s83, 31
	v_writelane_b32 v255, s84, 32
	v_writelane_b32 v255, s85, 33
	v_writelane_b32 v255, s86, 34
	v_writelane_b32 v255, s87, 35
	s_cbranch_vccnz .LBB0_301
	v_and_b32_e32 v0, 63, v254
	v_lshrrev_b32_e32 v1, 6, v254
	v_and_b32_e32 v120, 7, v0
	v_bfe_u32 v121, v0, 3, 3
	v_add_u32_e32 v122, 0, v1
	v_and_b32_e32 v123, 3, v122
	v_lshl_add_u32 v123, v123, 3, v120
	v_lshlrev_b32_e32 v2, 2, v123
	v_lshrrev_b32_e32 v122, 2, v122
	v_lshl_add_u32 v122, v122, 3, v121
	v_lshlrev_b32_e32 v4, 2, v122
	v_lshlrev_b32_e32 v8, 2, v4
	v_lshlrev_b32_e32 v6, 2, v4
	v_lshlrev_b32_e32 v10, 2, v2
	v_lshlrev_b32_e32 v12, 1, v2
	v_add_u32_e32 v122, 8, v1
	v_and_b32_e32 v123, 3, v122
	v_lshl_add_u32 v123, v123, 3, v120
	v_lshlrev_b32_e32 v3, 2, v123
	v_lshrrev_b32_e32 v122, 2, v122
	v_lshl_add_u32 v122, v122, 3, v121
	v_lshlrev_b32_e32 v5, 2, v122
	v_lshlrev_b32_e32 v9, 2, v5
	v_lshlrev_b32_e32 v7, 2, v5
	v_lshlrev_b32_e32 v11, 2, v3
	v_lshlrev_b32_e32 v13, 1, v3
	s_mov_b32 s35, s18
	s_cmpk_lt_u32 s35, 0x9d0
	s_cbranch_scc0 .Lwc_done
	s_cmpk_lt_u32 s35, 0x580
	s_cbranch_scc0 .Lwc_p1_a0
	s_mov_b32 s21, 0
	s_mov_b32 s22, s35
	s_cmpk_lt_u32 s22, 0x160
	s_cbranch_scc1 .Lwc_gu_a0
	s_sub_u32 s22, s22, 0x160
	s_add_u32 s21, s21, 1
	s_cmpk_lt_u32 s22, 0x160
	s_cbranch_scc1 .Lwc_gu_a0
	s_sub_u32 s22, s22, 0x160
	s_add_u32 s21, s21, 1
	s_cmpk_lt_u32 s22, 0x160
	s_cbranch_scc1 .Lwc_gu_a0
	s_sub_u32 s22, s22, 0x160
	s_add_u32 s21, s21, 1
.Lwc_gu_a0:
	s_lshr_b32 s23, s22, 3
	s_and_b32 s22, s22, 7
	s_and_b32 s30, s21, 1
	s_lshr_b32 s31, s21, 1
	s_cmp_eq_u32 s30, 0
	s_cselect_b32 s24, s60, s68
	s_cselect_b32 s25, s61, s69
	s_cselect_b32 s28, s58, s66
	s_cselect_b32 s29, s59, s67
	s_mul_i32 s30, s31, 0x1600000
	s_add_u32 s24, s24, s30
	s_addc_u32 s25, s25, 0
	s_lshl_b32 s30, s31, 12
	s_add_u32 s28, s28, s30
	s_addc_u32 s29, s29, 0
	s_mul_i32 s30, s21, 0xb00000
	s_add_u32 s26, s88, s30
	s_addc_u32 s27, s89, 0
	s_and_b32 s30, s23, 1
	s_mul_i32 s30, s30, 0x2c00
	s_lshr_b32 s31, s23, 1
	s_lshl_b32 s31, s31, 9
	s_add_u32 s30, s30, s31
	s_add_u32 s24, s24, s30
	s_addc_u32 s25, s25, 0
	s_mul_i32 s30, s22, 0x2c0000
	s_add_u32 s2, s24, s30
	s_addc_u32 s3, s25, 0
	s_mul_i32 s30, s23, 0x40000
	s_lshl_b32 s31, s22, 8
	s_add_u32 s30, s30, s31
	s_add_u32 s6, s26, s30
	s_addc_u32 s7, s27, 0
	s_lshl_b32 s30, s22, 9
	s_add_u32 s8, s28, s30
	s_addc_u32 s9, s29, 0
	s_mov_b32 s15, 1
	s_mov_b32 s10, 0x5800
	s_mov_b32 s11, 0x800
	s_mov_b64 s[12:13], 0
	s_mov_b32 s14, 0x7fffffff
	s_branch .Lwc_pdone_a0

; __device__ __forceinline__ int opq_bid() { int b = blockIdx.x; asm volatile("" : "+s"(b)); return b; }
; __device__ __forceinline__ f32x4 ld_nt(const float* p) { return __builtin_nontemporal_load((const f32x4*)p); }
; __device__ __forceinline__ void convert_weight_v4(LAS unsigned char* lds, const float* W, bf16_t* Bt, int K, int Nsrc, int Ndst, const float* gain, int mode) {
;     ...
;     for (int t = opq_bid(); t < nkt * nnt; t += gridDim.x) {
;         const int k0 = (t % nkt) * 64, pn = t / nkt, n0 = pn * 256;
;         f32x4 v[8];
; #pragma unroll
;         for (int i = 0; i < 8; ++i) {
;             const int e = tid + i * 512, kk = e >> 6, n4 = e & 63;
;             const int n = (mode == 1) ? (n4 >> 5) * FF + pn * 128 + (n4 & 31) * 4 : n0 + n4 * 4;
;             v[i] = (f32x4){0.f, 0.f, 0.f, 0.f};
;             if (n < Nsrc) v[i] = ld_nt(W + (size_t)(k0 + kk) * Nsrc + n);
; __device__ __forceinline__ void prologue(LAS unsigned char* lds, const Params& P) {
;     ...
;         convert_weight_v4(lds, in[10] + (size_t)l * D * 2 * FF, (bf16_t*)(ws + W_GU + (size_t)(l * 2 + 0) * W_GU_SZ), D, 2 * FF, 2 * FF, in[9] + l * D, 1);
;         convert_weight_v4(lds, in[14] + (size_t)l * D * 2 * FF, (bf16_t*)(ws + W_GU + (size_t)(l * 2 + 1) * W_GU_SZ), D, 2 * FF, 2 * FF, in[13] + l * D, 1);
;         convert_weight_v4(lds, in[11] + (size_t)l * FF * D, (bf16_t*)(ws + W_DN + (size_t)(l * 2 + 0) * W_DN_SZ), FF, D, D, nullptr, 0);
;         convert_weight_v4(lds, in[15] + (size_t)l * FF * D, (bf16_t*)(ws + W_DN + (size_t)(l * 2 + 1) * W_DN_SZ), FF, D, D, nullptr, 0);
;     }
;     convert_weight_v4(lds, in[16], (bf16_t*)(ws + W_IN0), D, 3072, 3072, in[12], 0);
;     convert_weight_v4(lds, in[23], (bf16_t*)(ws + W_OUT0), D, D, D, nullptr, 0);
;     convert_weight_v4(lds, in[24], (bf16_t*)(ws + W_IN1), D, 672, 768, in[12] + D, 0);
;     convert_weight(lds, in[27], (bf16_t*)(ws + W_QUP), 384, 1536, 1536, in[25], 2);
;     convert_weight_v4(lds, in[28], (bf16_t*)(ws + W_KVUP), 256, 2048, 2048, nullptr, 0);
;     convert_weight_v4(lds, in[29], (bf16_t*)(ws + W_OUT1), D, D, D, nullptr, 0);
.Lwc_dn_a0:
	s_and_b32 s23, s22, 7
	s_lshr_b32 s22, s22, 3
	s_and_b32 s30, s21, 1
	s_lshr_b32 s31, s21, 1
	s_cmp_eq_u32 s30, 0
	s_cselect_b32 s24, s62, s70
	s_cselect_b32 s25, s63, s71
	s_mul_i32 s30, s31, 0xb00000
	s_add_u32 s24, s24, s30
	s_addc_u32 s25, s25, 0
	s_mul_i32 s30, s21, 0x580000
	s_add_u32 s30, s30, 0x2c00000
	s_add_u32 s26, s88, s30
	s_addc_u32 s27, s89, 0
	s_lshl_b32 s30, s23, 9
	s_add_u32 s24, s24, s30
	s_addc_u32 s25, s25, 0
	s_mul_i32 s30, s22, 0x80000
	s_add_u32 s2, s24, s30
	s_addc_u32 s3, s25, 0
	s_mul_i32 s30, s23, 0xb0000
	s_lshl_b32 s31, s22, 8
	s_add_u32 s30, s30, s31
	s_add_u32 s6, s26, s30
	s_addc_u32 s7, s27, 0
	s_mov_b64 s[8:9], s[2:3]
	s_mov_b32 s15, 0
	s_mov_b32 s10, 0x1000
	s_mov_b32 s11, 0x1600
	s_mov_b64 s[12:13], 0
	s_mov_b32 s14, 0x7fffffff
	s_branch .Lwc_pdone_a0
.Lwc_p2_a0:
	s_cmpk_lt_u32 s35, 0x900
	s_cbranch_scc0 .Lwc_p3_a0
	s_sub_u32 s22, s35, 0x840
	s_lshr_b32 s23, s22, 3
	s_and_b32 s22, s22, 7
	s_lshl_b32 s30, s23, 9
	s_add_u32 s24, s72, s30
	s_addc_u32 s25, s73, 0
	s_mov_b64 s[28:29], s[64:65]
	s_add_u32 s26, s88, 0x4200000
	s_addc_u32 s27, s89, 0
	s_mul_i32 s30, s22, 0x180000
	s_add_u32 s2, s24, s30
	s_addc_u32 s3, s25, 0
	s_mul_i32 s30, s23, 0x40000
	s_lshl_b32 s31, s22, 8
	s_add_u32 s30, s30, s31
	s_add_u32 s6, s26, s30
	s_addc_u32 s7, s27, 0
	s_lshl_b32 s30, s22, 9
	s_add_u32 s8, s28, s30
	s_addc_u32 s9, s29, 0
	s_mov_b32 s15, 1
	s_mov_b32 s10, 0x3000
	s_mov_b32 s11, 0x800
	s_mov_b64 s[12:13], 0
	s_mov_b32 s14, 0x7fffffff
	s_branch .Lwc_pdone_a0
.Lwc_p3_a0:
	s_cmpk_lt_u32 s35, 0x940
	s_cbranch_scc0 .Lwc_p4_a0
	s_sub_u32 s22, s35, 0x900
	s_lshr_b32 s23, s22, 3
	s_and_b32 s22, s22, 7
	s_lshl_b32 s30, s23, 9
	s_add_u32 s24, s86, s30
	s_addc_u32 s25, s87, 0
	s_add_u32 s26, s88, 0x4800000
	s_addc_u32 s27, s89, 0
	s_mul_i32 s30, s22, 0x80000
	s_add_u32 s2, s24, s30
	s_addc_u32 s3, s25, 0
	s_mul_i32 s30, s23, 0x40000
	s_lshl_b32 s31, s22, 8
	s_add_u32 s30, s30, s31
	s_add_u32 s6, s26, s30
	s_addc_u32 s7, s27, 0
	s_mov_b64 s[8:9], s[2:3]
	s_mov_b32 s15, 0
	s_mov_b32 s10, 0x1000
	s_mov_b32 s11, 0x800
	s_mov_b64 s[12:13], 0
	s_mov_b32 s14, 0x7fffffff
	s_branch .Lwc_pdone_a0
.Lwc_p4_a0:
	s_cmpk_lt_u32 s35, 0x970
	s_cbranch_scc0 .Lwc_p5_a0
	s_sub_u32 s22, s35, 0x940
	s_lshr_b32 s23, s22, 3
	s_and_b32 s22, s22, 7
	s_lshl_b32 s30, s23, 9
	s_add_u32 s24, s40, s30
	s_addc_u32 s25, s41, 0
	s_add_u32 s28, s64, 0x1000
	s_addc_u32 s29, s65, 0
	s_add_u32 s26, s88, 0x4a00000
	s_addc_u32 s27, s89, 0
	s_mul_i32 s30, s22, 0x54000
	s_add_u32 s2, s24, s30
	s_addc_u32 s3, s25, 0
	s_mul_i32 s30, s23, 0x40000
	s_lshl_b32 s31, s22, 8
	s_add_u32 s30, s30, s31
	s_add_u32 s6, s26, s30
	s_addc_u32 s7, s27, 0
	s_lshl_b32 s30, s22, 9
	s_add_u32 s8, s28, s30
	s_addc_u32 s9, s29, 0
	s_mov_b32 s15, 1
	s_mov_b32 s10, 0xa80
	s_mov_b32 s11, 0x800
	s_mov_b64 s[12:13], 0
	s_lshl_b32 s30, s23, 7
	s_sub_u32 s14, 0x2a0, s30
	s_branch .Lwc_pdone_a0
.Lwc_p5_a0:
	s_cmpk_lt_u32 s35, 0x990
	s_cbranch_scc0 .Lwc_p6_a0
	s_sub_u32 s22, s35, 0x970
	s_lshr_b32 s23, s22, 1
	s_and_b32 s22, s22, 1
	s_lshl_b32 s30, s23, 9
	s_add_u32 s24, s48, s30
	s_addc_u32 s25, s49, 0
	s_add_u32 s26, s88, 0x4ca0000
	s_addc_u32 s27, s89, 0
	s_mul_i32 s30, s22, 0x100000
	s_add_u32 s2, s24, s30
	s_addc_u32 s3, s25, 0
	s_mul_i32 s30, s23, 0x10000
	s_lshl_b32 s31, s22, 8
	s_add_u32 s30, s30, s31
	s_add_u32 s6, s26, s30
	s_addc_u32 s7, s27, 0
	s_mov_b64 s[8:9], s[2:3]
	s_mov_b32 s15, 0
	s_mov_b32 s10, 0x2000
	s_mov_b32 s11, 0x200
	s_mov_b64 s[12:13], 0
	s_mov_b32 s14, 0x7fffffff
	s_branch .Lwc_pdone_a0
.Lwc_p6_a0:
	s_sub_u32 s22, s35, 0x990
	s_lshr_b32 s23, s22, 3
	s_and_b32 s22, s22, 7
	s_lshl_b32 s30, s23, 9
	s_add_u32 s24, s50, s30
	s_addc_u32 s25, s51, 0
	s_add_u32 s26, s88, 0x4da0000
	s_addc_u32 s27, s89, 0
	s_mul_i32 s30, s22, 0x80000
	s_add_u32 s2, s24, s30
	s_addc_u32 s3, s25, 0
	s_mul_i32 s30, s23, 0x40000
	s_lshl_b32 s31, s22, 8
	s_add_u32 s30, s30, s31
	s_add_u32 s6, s26, s30
	s_addc_u32 s7, s27, 0
	s_mov_b64 s[8:9], s[2:3]
	s_mov_b32 s15, 0
	s_mov_b32 s10, 0x1000
	s_mov_b32 s11, 0x800
	s_mov_b64 s[12:13], 0
	s_mov_b32 s14, 0x7fffffff
	s_branch .Lwc_pdone_a0
